# v25 with P6 processing its two row-panel rounds in reverse order (row panels whose FFN activations were written last in P5 first)
# baseline (speedup 1.0000x reference)
;     __host__ __device__ bool next(int i, Unit& u) const {
;         const long L = (long)i * G + c; if (L >= nwg) return false;
;         int wgid = (int)L; { const int q = nwg / NXCD, r = nwg % NXCD, xcd = wgid % NXCD, off = wgid / NXCD; wgid = (xcd < r ? xcd * (q + 1) : r * (q + 1) + (xcd - r) * q) + off; }
;         const int nig = WGM * nN, gid = wgid / nig, fm = gid * WGM, gsz = (nM - fm) < WGM ? (nM - fm) : WGM;
;         u.pm = fm + ((wgid % nig) % gsz); u.pn = (wgid % nig) / gsz; return true;
; template <class Epi, class Sched, bool ALIGN_EPI = false, bool SP2 = false>
; __device__ __forceinline__ void gemm_phase(PG8_LAS unsigned char* lds, const Gemm g, const Sched& S, const Epi& E) {
;     ...
;     if (!S.next(0, cur)) return;
.LBB0_659:
	s_andn2_b64 vcc, exec, s[2:3]
	s_cbranch_vccnz .LBB0_710
	s_cmpk_lt_i32 s96, 0x200
	s_cselect_b64 s[0:1], -1, 0
	s_cmpk_gt_i32 s96, 0x1ff
	v_readfirstlane_b32 s4, v207
	s_cbranch_scc1 .LBB0_666
	s_xor_b32 s98, s96, 0x100
	s_ashr_i32 s2, s98, 31
	s_lshr_b32 s2, s2, 29
	s_add_i32 s5, s98, s2
	s_and_b32 s2, s5, -8
	s_sub_i32 s6, s98, s2
	s_cmp_gt_i32 s6, -1
	s_cbranch_scc0 .LBB0_663
	s_lshl_b32 s7, s6, 6
	s_cbranch_execz .LBB0_664
	s_branch .LBB0_665

;     __host__ __device__ bool next(int i, Unit& u) const {
;         const long L = (long)i * G + c; if (L >= nwg) return false;
;         int wgid = (int)L; { const int q = nwg / NXCD, r = nwg % NXCD, xcd = wgid % NXCD, off = wgid / NXCD; wgid = (xcd < r ? xcd * (q + 1) : r * (q + 1) + (xcd - r) * q) + off; }
;         const int nig = WGM * nN, gid = wgid / nig, fm = gid * WGM, gsz = (nM - fm) < WGM ? (nM - fm) : WGM;
;         u.pm = fm + ((wgid % nig) % gsz); u.pn = (wgid % nig) / gsz; return true;
; template <class Epi, class Sched, bool ALIGN_EPI = false, bool SP2 = false>
; __device__ __forceinline__ void gemm_phase(PG8_LAS unsigned char* lds, const Gemm g, const Sched& S, const Epi& E) {
;     ...
;         const bool has_next = S.next(ui + 1, nxt);
.LBB0_672:
	s_add_i32 s46, s46, 1
	s_lshl_b64 s[0:1], s[46:47], 8
	s_add_u32 s4, s0, s96
	s_addc_u32 s5, s1, s63
	s_cmp_lt_u32 s4, 0x200
	s_cselect_b32 s98, 0x100, 0
	s_xor_b32 s4, s4, s98
	v_cmp_gt_i64_e32 vcc, s[4:5], v[150:151]
	v_cmp_lt_i64_e64 s[0:1], s[4:5], v[148:149]
	s_cbranch_vccnz .LBB0_678
	s_ashr_i32 s5, s4, 31
	s_lshr_b32 s5, s5, 29
	s_add_i32 s12, s4, s5
	s_and_b32 s5, s12, -8
	s_sub_i32 s13, s4, s5
	s_cmp_gt_i32 s13, -1
	s_mov_b64 s[4:5], -1
	s_cbranch_scc0 .LBB0_675
	s_lshl_b32 s16, s13, 6
	s_mov_b64 s[4:5], 0

; __global__ void __launch_bounds__(NWAVES * 64, 2) fwd_kernel(Args args) {
	.amdhsa_kernel _Z10fwd_kernel4Args
		.amdhsa_group_segment_fixed_size 0
		.amdhsa_private_segment_fixed_size 0
		.amdhsa_kernarg_size 416
		.amdhsa_user_sgpr_count 2
		.amdhsa_user_sgpr_dispatch_ptr 0
		.amdhsa_user_sgpr_queue_ptr 0
		.amdhsa_user_sgpr_kernarg_segment_ptr 1
		.amdhsa_user_sgpr_dispatch_id 0
		.amdhsa_user_sgpr_kernarg_preload_length 0
		.amdhsa_user_sgpr_kernarg_preload_offset 0
		.amdhsa_user_sgpr_private_segment_size 0
		.amdhsa_uses_dynamic_stack 0
		.amdhsa_enable_private_segment 0
		.amdhsa_system_sgpr_workgroup_id_x 1
		.amdhsa_system_sgpr_workgroup_id_y 0
		.amdhsa_system_sgpr_workgroup_id_z 0
		.amdhsa_system_sgpr_workgroup_info 0
		.amdhsa_system_vgpr_workitem_id 2
		.amdhsa_next_free_vgpr 239
		.amdhsa_next_free_sgpr 102
		.amdhsa_accum_offset 240
		.amdhsa_reserve_vcc 1
		.amdhsa_float_round_mode_32 0
		.amdhsa_float_round_mode_16_64 0
		.amdhsa_float_denorm_mode_32 3
		.amdhsa_float_denorm_mode_16_64 3
		.amdhsa_dx10_clamp 1
		.amdhsa_ieee_mode 1
		.amdhsa_fp16_overflow 0
		.amdhsa_tg_split 0
		.amdhsa_exception_fp_ieee_invalid_op 0
		.amdhsa_exception_fp_denorm_src 0
		.amdhsa_exception_fp_ieee_div_zero 0
		.amdhsa_exception_fp_ieee_overflow 0
		.amdhsa_exception_fp_ieee_underflow 0
		.amdhsa_exception_fp_ieee_inexact 0
		.amdhsa_exception_int_div_zero 0
	.end_amdhsa_kernel

; __global__ void __launch_bounds__(NWAVES * 64, 2) fwd_kernel(Args args) {
amdhsa.kernels:
  - .agpr_count:     0
    .args:
      - .offset:         0
        .size:           160
        .value_kind:     by_value
      - .offset:         160
        .size:           4
        .value_kind:     hidden_block_count_x
      - .offset:         164
        .size:           4
        .value_kind:     hidden_block_count_y
      - .offset:         168
        .size:           4
        .value_kind:     hidden_block_count_z
      - .offset:         172
        .size:           2
        .value_kind:     hidden_group_size_x
      - .offset:         174
        .size:           2
        .value_kind:     hidden_group_size_y
      - .offset:         176
        .size:           2
        .value_kind:     hidden_group_size_z
      - .offset:         178
        .size:           2
        .value_kind:     hidden_remainder_x
      - .offset:         180
        .size:           2
        .value_kind:     hidden_remainder_y
      - .offset:         182
        .size:           2
        .value_kind:     hidden_remainder_z
      - .offset:         200
        .size:           8
        .value_kind:     hidden_global_offset_x
      - .offset:         208
        .size:           8
        .value_kind:     hidden_global_offset_y
      - .offset:         216
        .size:           8
        .value_kind:     hidden_global_offset_z
      - .offset:         224
        .size:           2
        .value_kind:     hidden_grid_dims
      - .offset:         248
        .size:           8
        .value_kind:     hidden_multigrid_sync_arg
      - .offset:         280
        .size:           4
        .value_kind:     hidden_dynamic_lds_size
    .group_segment_fixed_size: 0
    .kernarg_segment_align: 8
    .kernarg_segment_size: 416
    .language:       OpenCL C
    .language_version:
      - 2
      - 0
    .max_flat_workgroup_size: 512
    .name:           _Z10fwd_kernel4Args
    .private_segment_fixed_size: 0
    .sgpr_count:     108
    .sgpr_spill_count: 11
    .symbol:         _Z10fwd_kernel4Args.kd
    .uniform_work_group_size: 1
    .uses_dynamic_stack: false
    .vgpr_count:     239
    .vgpr_spill_count: 0
    .wavefront_size: 64
